# conv phase rewritten by hand (all loads of an 8-token half in flight before the first wait instead of 2 serialized round trips per token); attention Q-row staging loads issued together
# baseline (speedup 1.0000x reference)
; #define LAS __attribute__((address_space(3)))
; #define LDS_BARRIER() asm volatile("s_waitcnt lgkmcnt(0)\n\ts_barrier" ::: "memory")
; #define ATT_STORE(K0, K1, V0, V1, buf) do { LAS unsigned char* kp_ = lds + KB0 + (buf) * 64 * KST + srow * KST + scb; *(LAS bf16x8*)kp_ = K0; *(LAS bf16x8*)(kp_ + 32 * KST) = K1; \
;         LAS unsigned char* vp_ = lds + VB0 + (buf) * 64 * VST + srow * VST + scb; *(LAS bf16x8*)vp_ = V0; *(LAS bf16x8*)(vp_ + 32 * VST) = V1; } while (0)
; __device__ __forceinline__ void attn_phase(LAS unsigned char* lds, const bf16* QH, const bf16* KH, const bf16* VH, const float* rpb, bf16* MIX, int G, int bid, int tid) {
;     ...
;         const int rwa = r0 + 2 * rp, r = rwa + lr;
;         const int rs = clampi(r - 4, 0, 24), rsa = clampi(rwa - 4, 0, 24), rsb = clampi(rwa - 3, 0, 24);
;         LAS unsigned char* qreg = lds + QB0 + wave * (32 * KST);
;         {
; #pragma unroll
;           for (int j = 0; j < 8; ++j) { const int chunk = j * 64 + lane, row = chunk >> 4, c = chunk & 15;
;               const bf16x8 v = *(const bf16x8*)(QH + ((size_t)(b * 8 + h) * 2048 + (rwa + (row >> 4)) * 64 + 16 * wj + (row & 15)) * 128 + c * 8);
;               *(LAS bf16x8*)(qreg + row * KST + c * 16) = v; } }
;         const LAS unsigned char* qbase = qreg + r32 * KST + 16 * hh;
;         f32x16 o[4];
; #pragma unroll
;         for (int db = 0; db < 4; ++db)
; #pragma unroll
;             for (int e = 0; e < 16; ++e) o[db][e] = 0.f;
;         float m = -3.0e38f, l = 0.f;
;         const LAS unsigned char* kbase = lds + KB0 + r32 * KST + 16 * hh;
;         const LAS unsigned char* vbase = lds + VB0 + (4 * hh + ((lane & 15) >> 2)) * VST + (16 * ((lane >> 4) & 1) + 4 * (lane & 3)) * 2;
;     ...
;         ATT_STORE(ak0, ak1, av0, av1, 0);
;         LDS_BARRIER();
.LBB0_202:
	s_or_b64 exec, exec, s[44:45]
	s_add_i32 s44, s90, s94
	s_lshl_b64 s[46:47], s[46:47], 11
	s_lshl_b32 s5, s44, 6
	s_or_b64 s[46:47], s[46:47], s[70:71]
	s_ashr_i32 s45, s5, 31
	s_add_u32 s63, s46, s5
	s_addc_u32 s45, s47, s45
	v_mov_b32_e32 v35, s45
	v_or_b32_e32 v34, s63, v174
	v_lshlrev_b64 v[34:35], 8, v[34:35]
	v_lshl_add_u64 v[34:35], v[170:171], 0, v[34:35]
	global_load_dwordx4 v[2:5], v[34:35], off
	v_mov_b32_e32 v35, s45
	v_or_b32_e32 v34, s63, v176
	v_lshlrev_b64 v[34:35], 8, v[34:35]
	v_lshl_add_u64 v[34:35], v[170:171], 0, v[34:35]
	global_load_dwordx4 v[6:9], v[34:35], off
	v_mov_b32_e32 v35, s45
	v_or_b32_e32 v34, s63, v178
	v_lshlrev_b64 v[34:35], 8, v[34:35]
	v_lshl_add_u64 v[34:35], v[170:171], 0, v[34:35]
	global_load_dwordx4 v[10:13], v[34:35], off
	v_mov_b32_e32 v35, s45
	v_or_b32_e32 v34, s63, v180
	v_lshlrev_b64 v[34:35], 8, v[34:35]
	v_lshl_add_u64 v[34:35], v[170:171], 0, v[34:35]
	global_load_dwordx4 v[14:17], v[34:35], off
	s_or_b32 s5, s5, 64
	s_mov_b32 s99, 0
	s_ashr_i32 s45, s5, 31
	s_add_u32 s5, s46, s5
	s_addc_u32 s45, s47, s45
	v_mov_b32_e32 v35, s45
	v_or_b32_e32 v34, s5, v174
	v_lshlrev_b64 v[34:35], 8, v[34:35]
	v_lshl_add_u64 v[34:35], v[170:171], 0, v[34:35]
	global_load_dwordx4 v[18:21], v[34:35], off
	v_mov_b32_e32 v35, s45
	v_or_b32_e32 v34, s5, v176
	v_lshlrev_b64 v[34:35], 8, v[34:35]
	v_lshl_add_u64 v[34:35], v[170:171], 0, v[34:35]
	global_load_dwordx4 v[22:25], v[34:35], off
	v_mov_b32_e32 v35, s45
	v_or_b32_e32 v34, s5, v178
	v_lshlrev_b64 v[34:35], 8, v[34:35]
	v_lshl_add_u64 v[34:35], v[170:171], 0, v[34:35]
	global_load_dwordx4 v[26:29], v[34:35], off
	v_mov_b32_e32 v35, s45
	v_or_b32_e32 v34, s5, v180
	v_lshlrev_b64 v[34:35], 8, v[34:35]
	v_lshl_add_u64 v[34:35], v[170:171], 0, v[34:35]
	global_load_dwordx4 v[30:33], v[34:35], off
	s_cmp_lt_i32 s64, -3
	s_waitcnt vmcnt(7)
	ds_write_b128 v188, v[2:5]
	s_waitcnt vmcnt(6)
	ds_write_b128 v188, v[6:9] offset:1088
	s_waitcnt vmcnt(5)
	ds_write_b128 v188, v[10:13] offset:2176
	s_waitcnt vmcnt(4)
	ds_write_b128 v188, v[14:17] offset:3264
	s_waitcnt vmcnt(3)
	ds_write_b128 v188, v[18:21] offset:4352
	s_waitcnt vmcnt(2)
	ds_write_b128 v188, v[22:25] offset:5440
	s_waitcnt vmcnt(1)
	ds_write_b128 v188, v[26:29] offset:6528
	s_waitcnt vmcnt(0)
	ds_write_b128 v188, v[30:33] offset:7616
	ds_write_b128 v189, v[132:135]
	ds_write_b128 v189, v[136:139] offset:8704
	ds_write_b128 v172, v[140:143] offset:34816
	ds_write_b128 v172, v[148:151] offset:45056
	s_waitcnt lgkmcnt(0)
	s_barrier
	s_cbranch_scc1 .LBB0_244
	s_add_i32 s5, s44, -4
	s_min_u32 s5, s5, 24
	s_cmp_gt_i32 s44, 3
	s_cselect_b32 s5, s5, 0
	s_add_i32 s45, s44, -3
	s_min_u32 s45, s45, 24
	s_add_i32 s63, s64, 4
	s_add_i32 s45, s45, 8
	s_cmp_gt_i32 s44, 2
	v_or_b32_e32 v1, s44, v167
	s_cselect_b32 s89, s45, 8
	s_lshl_b32 s44, s80, 6
	s_sub_i32 s44, s81, s44
	s_mov_b64 s[60:61], s[86:87]
	s_add_i32 s86, s44, 0x8c0
	s_mul_i32 s44, s79, 31
	s_and_b32 s45, s51, 7
	s_add_i32 s51, s62, s44
	s_mul_i32 s44, s79, 0x7c
	v_add_u32_e32 v2, -4, v1
	v_cmp_lt_i32_e32 vcc, 3, v1
	s_mul_i32 s46, s45, 0x7c
	v_add_u32_e32 v1, s44, v186
	s_mulk_i32 s45, 0x1f0
	v_subrev_u32_e32 v193, s45, v1
	v_mul_i32_i24_e32 v1, 0xffffffe1, v167
	v_min_u32_e32 v2, 24, v2
	v_subrev_u32_e32 v1, s46, v1
	v_mov_b32_e32 v14, v0
	v_mov_b32_e32 v15, v0
	v_cndmask_b32_e32 v131, 0, v2, vcc
	v_add_u32_e32 v191, s51, v1
	v_mov_b32_e32 v1, v0
	v_mov_b32_e32 v2, v0
	v_mov_b32_e32 v3, v0
	v_mov_b32_e32 v4, v0
	v_mov_b32_e32 v5, v0
	v_mov_b32_e32 v6, v0
	v_mov_b32_e32 v7, v0
	v_mov_b32_e32 v8, v0
	v_mov_b32_e32 v9, v0
	v_mov_b32_e32 v10, v0
	v_mov_b32_e32 v11, v0
	v_mov_b32_e32 v12, v0
	v_mov_b32_e32 v13, v0
	v_mov_b64_e32 v[64:65], v[14:15]
	v_mov_b64_e32 v[48:49], v[14:15]
	v_mov_b64_e32 v[32:33], v[14:15]
	v_mov_b64_e32 v[62:63], v[12:13]
	v_mov_b64_e32 v[60:61], v[10:11]
	v_mov_b64_e32 v[58:59], v[8:9]
	v_mov_b64_e32 v[56:57], v[6:7]
	v_mov_b64_e32 v[54:55], v[4:5]
	v_mov_b64_e32 v[52:53], v[2:3]
	v_mov_b64_e32 v[50:51], v[0:1]
	v_mov_b64_e32 v[46:47], v[12:13]
	v_mov_b64_e32 v[44:45], v[10:11]
	v_mov_b64_e32 v[42:43], v[8:9]
	v_mov_b64_e32 v[40:41], v[6:7]
	v_mov_b64_e32 v[38:39], v[4:5]
	v_mov_b64_e32 v[36:37], v[2:3]
	v_mov_b64_e32 v[34:35], v[0:1]
	v_mov_b64_e32 v[30:31], v[12:13]
	v_mov_b64_e32 v[28:29], v[10:11]
	v_mov_b64_e32 v[26:27], v[8:9]
	v_mov_b64_e32 v[24:25], v[6:7]
	v_mov_b64_e32 v[22:23], v[4:5]
	v_mov_b64_e32 v[20:21], v[2:3]
	v_mov_b64_e32 v[18:19], v[0:1]
	v_mov_b64_e32 v[16:17], v[14:15]
	s_mov_b32 s65, 3
	v_add_u32_e32 v190, 8, v131
	v_subrev_u32_e32 v192, s46, v185
	v_mov_b32_e32 v195, 0xff61b1e6
	v_mov_b32_e32 v130, 0
	v_mov_b32_e32 v194, v187
	v_mov_b64_e32 v[14:15], v[12:13]
	v_mov_b64_e32 v[12:13], v[10:11]
	v_mov_b64_e32 v[10:11], v[8:9]
	v_mov_b64_e32 v[8:9], v[6:7]
	v_mov_b64_e32 v[6:7], v[4:5]
	v_mov_b64_e32 v[4:5], v[2:3]
	v_mov_b64_e32 v[2:3], v[0:1]

; __device__ __forceinline__ void conv_phase(const bf16* BCU, const float* conv_w, bf16* MIX, int G, int bid, int tid) {
;     ...
;     for (int it = bid * NTHR + tid; it < (MTOK / 16) * 128; it += nthreads) {
;         const int chg = it & 127, run = it >> 7, ch = 8 * chg, t0 = run * 16, tl0 = t0 & (SEQ - 1);
;         float w0[8], w1[8], w2[8];
; #pragma unroll
;         for (int e = 0; e < 8; ++e) { w0[e] = conv_w[ch + e]; w1[e] = conv_w[1024 + ch + e]; w2[e] = conv_w[2048 + ch + e]; }
;         const bf16* base = BCU + (size_t)t0 * 3072 + ch;
;         float zp[8], zc[8], zn[8];
;     ...
;         if (tl0 > 0) CONV_Z(zp, -1); else {
; #pragma unroll
;             for (int e = 0; e < 8; ++e) zp[e] = 0.f; }
;         CONV_Z(zc, 0);
; #pragma unroll 4
;         for (int i = 0; i < 16; ++i) {
;             if (tl0 + i + 1 < SEQ) CONV_Z(zn, i + 1); else {
; #pragma unroll
;                 for (int e = 0; e < 8; ++e) zn[e] = 0.f; }
;             const v4u bb = *(const v4u*)(base + (size_t)i * 3072);
.LBB0_248:
	v_mov_b32_e32 v152, v74
	v_and_b32_e32 v1, 0x7f, v74
	v_lshlrev_b32_e32 v2, 5, v1
	v_add_u32_e32 v3, 0x1000, v2
	v_add_u32_e32 v4, 0x2000, v2
	global_load_dwordx4 v[8:11], v2, s[8:9]
	global_load_dwordx4 v[12:15], v2, s[8:9] offset:16
	global_load_dwordx4 v[16:19], v3, s[8:9]
	global_load_dwordx4 v[20:23], v3, s[8:9] offset:16
	global_load_dwordx4 v[24:27], v4, s[8:9]
	global_load_dwordx4 v[28:31], v4, s[8:9] offset:16
	v_ashrrev_i32_e32 v5, 7, v74
	v_lshlrev_b32_e32 v6, 4, v1
	v_mul_u32_u24_e32 v7, 0x18000, v5
	v_add_u32_e32 v7, v7, v6
	v_add_u32_e32 v7, 0x800, v7
	v_lshl_add_u32 v32, v5, 16, v6
	v_and_b32_e32 v33, 0x7f, v5
	s_add_u32 s14, s82, 0x26000000
	s_addc_u32 s15, s83, 0
	v_subrev_u32_e32 v34, 0x1800, v7
	v_readfirstlane_b32 s2, v33
	s_cmp_eq_u32 s2, 0
	s_cbranch_scc1 .Lcv_h0z
	global_load_dwordx4 v[36:39], v34, s[10:11]
	global_load_dwordx4 v[40:43], v34, s[10:11] offset:2048
	s_branch .Lcv_h0d
.Lcv_h0z:
	v_mov_b32_e32 v36, 0
	v_mov_b32_e32 v37, 0
	v_mov_b32_e32 v38, 0
	v_mov_b32_e32 v39, 0
	v_mov_b32_e32 v40, 0
	v_mov_b32_e32 v41, 0
	v_mov_b32_e32 v42, 0
	v_mov_b32_e32 v43, 0
.Lcv_h0d:
	global_load_dwordx4 v[44:47], v7, s[10:11]
	global_load_dwordx4 v[48:51], v7, s[10:11] offset:2048
	v_mov_b32_e32 v34, v7
	global_load_dwordx4 v[60:63], v34, s[10:11] offset:-2048
	v_add_u32_e32 v34, 0x1800, v34
	global_load_dwordx4 v[52:55], v34, s[10:11]
	global_load_dwordx4 v[56:59], v34, s[10:11] offset:2048
	global_load_dwordx4 v[72:75], v34, s[10:11] offset:-2048
	v_add_u32_e32 v34, 0x1800, v34
	global_load_dwordx4 v[64:67], v34, s[10:11]
	global_load_dwordx4 v[68:71], v34, s[10:11] offset:2048
	global_load_dwordx4 v[84:87], v34, s[10:11] offset:-2048
	v_add_u32_e32 v34, 0x1800, v34
	global_load_dwordx4 v[76:79], v34, s[10:11]
	global_load_dwordx4 v[80:83], v34, s[10:11] offset:2048
	global_load_dwordx4 v[96:99], v34, s[10:11] offset:-2048
	v_add_u32_e32 v34, 0x1800, v34
	global_load_dwordx4 v[88:91], v34, s[10:11]
	global_load_dwordx4 v[92:95], v34, s[10:11] offset:2048
	global_load_dwordx4 v[108:111], v34, s[10:11] offset:-2048
	v_add_u32_e32 v34, 0x1800, v34
	global_load_dwordx4 v[100:103], v34, s[10:11]
	global_load_dwordx4 v[104:107], v34, s[10:11] offset:2048
	global_load_dwordx4 v[120:123], v34, s[10:11] offset:-2048
	v_add_u32_e32 v34, 0x1800, v34
	global_load_dwordx4 v[112:115], v34, s[10:11]
	global_load_dwordx4 v[116:119], v34, s[10:11] offset:2048
	global_load_dwordx4 v[132:135], v34, s[10:11] offset:-2048
	v_add_u32_e32 v34, 0x1800, v34
	global_load_dwordx4 v[124:127], v34, s[10:11]
	global_load_dwordx4 v[128:131], v34, s[10:11] offset:2048
	global_load_dwordx4 v[144:147], v34, s[10:11] offset:-2048
	v_add_u32_e32 v34, 0x1800, v34
	global_load_dwordx4 v[136:139], v34, s[10:11]
	global_load_dwordx4 v[140:143], v34, s[10:11] offset:2048
	s_waitcnt vmcnt(0)
	v_lshlrev_b32_e32 v148, 16, v36
	v_and_b32_e32 v149, 0xffff0000, v36
	v_lshlrev_b32_e32 v150, 16, v40
	v_and_b32_e32 v151, 0xffff0000, v40
	v_mul_f32_e32 v36, v148, v150
	v_mul_f32_e32 v40, v149, v151
	v_lshlrev_b32_e32 v148, 16, v37
	v_and_b32_e32 v149, 0xffff0000, v37
	v_lshlrev_b32_e32 v150, 16, v41
	v_and_b32_e32 v151, 0xffff0000, v41
	v_mul_f32_e32 v37, v148, v150
	v_mul_f32_e32 v41, v149, v151
	v_lshlrev_b32_e32 v148, 16, v38
	v_and_b32_e32 v149, 0xffff0000, v38
	v_lshlrev_b32_e32 v150, 16, v42
	v_and_b32_e32 v151, 0xffff0000, v42
	v_mul_f32_e32 v38, v148, v150
	v_mul_f32_e32 v42, v149, v151
	v_lshlrev_b32_e32 v148, 16, v39
	v_and_b32_e32 v149, 0xffff0000, v39
	v_lshlrev_b32_e32 v150, 16, v43
	v_and_b32_e32 v151, 0xffff0000, v43
	v_mul_f32_e32 v39, v148, v150
	v_mul_f32_e32 v43, v149, v151
	v_lshlrev_b32_e32 v148, 16, v44
	v_and_b32_e32 v149, 0xffff0000, v44
	v_lshlrev_b32_e32 v150, 16, v48
	v_and_b32_e32 v151, 0xffff0000, v48
	v_mul_f32_e32 v44, v148, v150
	v_mul_f32_e32 v48, v149, v151
	v_lshlrev_b32_e32 v148, 16, v45
	v_and_b32_e32 v149, 0xffff0000, v45
	v_lshlrev_b32_e32 v150, 16, v49
	v_and_b32_e32 v151, 0xffff0000, v49
	v_mul_f32_e32 v45, v148, v150
	v_mul_f32_e32 v49, v149, v151
	v_lshlrev_b32_e32 v148, 16, v46
	v_and_b32_e32 v149, 0xffff0000, v46
	v_lshlrev_b32_e32 v150, 16, v50
	v_and_b32_e32 v151, 0xffff0000, v50
	v_mul_f32_e32 v46, v148, v150
	v_mul_f32_e32 v50, v149, v151
	v_lshlrev_b32_e32 v148, 16, v47
	v_and_b32_e32 v149, 0xffff0000, v47
	v_lshlrev_b32_e32 v150, 16, v51
	v_and_b32_e32 v151, 0xffff0000, v51
	v_mul_f32_e32 v47, v148, v150
	v_mul_f32_e32 v51, v149, v151
	v_lshlrev_b32_e32 v148, 16, v52
	v_and_b32_e32 v149, 0xffff0000, v52
	v_lshlrev_b32_e32 v150, 16, v56
	v_and_b32_e32 v151, 0xffff0000, v56
	v_mul_f32_e32 v52, v148, v150
	v_mul_f32_e32 v56, v149, v151
	v_lshlrev_b32_e32 v148, 16, v53
	v_and_b32_e32 v149, 0xffff0000, v53
	v_lshlrev_b32_e32 v150, 16, v57
	v_and_b32_e32 v151, 0xffff0000, v57
	v_mul_f32_e32 v53, v148, v150
	v_mul_f32_e32 v57, v149, v151
	v_lshlrev_b32_e32 v148, 16, v54
	v_and_b32_e32 v149, 0xffff0000, v54
	v_lshlrev_b32_e32 v150, 16, v58
	v_and_b32_e32 v151, 0xffff0000, v58
	v_mul_f32_e32 v54, v148, v150
	v_mul_f32_e32 v58, v149, v151
	v_lshlrev_b32_e32 v148, 16, v55
	v_and_b32_e32 v149, 0xffff0000, v55
	v_lshlrev_b32_e32 v150, 16, v59
	v_and_b32_e32 v151, 0xffff0000, v59
	v_mul_f32_e32 v55, v148, v150
	v_mul_f32_e32 v59, v149, v151
	v_lshlrev_b32_e32 v148, 16, v64
	v_and_b32_e32 v149, 0xffff0000, v64
	v_lshlrev_b32_e32 v150, 16, v68
	v_and_b32_e32 v151, 0xffff0000, v68
	v_mul_f32_e32 v64, v148, v150
	v_mul_f32_e32 v68, v149, v151
	v_lshlrev_b32_e32 v148, 16, v65
	v_and_b32_e32 v149, 0xffff0000, v65
	v_lshlrev_b32_e32 v150, 16, v69
	v_and_b32_e32 v151, 0xffff0000, v69
	v_mul_f32_e32 v65, v148, v150
; __device__ __forceinline__ unsigned pkbf(float lo, float hi) { return pg8::cvt_pk_bf16(lo, hi); }
; __device__ __forceinline__ float bflo(unsigned w) { return __uint_as_float(w << 16); }
; __device__ __forceinline__ float bfhi(unsigned w) { return __uint_as_float(w & 0xffff0000u); }
; __device__ __forceinline__ void conv_phase(const bf16* BCU, const float* conv_w, bf16* MIX, int G, int bid, int tid) {
;     ...
;             for (int e = 0; e < 8; ++e) y[e] = w0[e] * zp[e] + w1[e] * zc[e] + w2[e] * zn[e];
;             v4u o; o.x = pkbf(bflo(bb.x) * y[0], bfhi(bb.x) * y[1]); o.y = pkbf(bflo(bb.y) * y[2], bfhi(bb.y) * y[3]);
;             o.z = pkbf(bflo(bb.z) * y[4], bfhi(bb.z) * y[5]); o.w = pkbf(bflo(bb.w) * y[6], bfhi(bb.w) * y[7]);
	v_mul_f32_e32 v69, v149, v151
	v_lshlrev_b32_e32 v148, 16, v66
	v_and_b32_e32 v149, 0xffff0000, v66
	v_lshlrev_b32_e32 v150, 16, v70
	v_and_b32_e32 v151, 0xffff0000, v70
	v_mul_f32_e32 v66, v148, v150
	v_mul_f32_e32 v70, v149, v151
	v_lshlrev_b32_e32 v148, 16, v67
	v_and_b32_e32 v149, 0xffff0000, v67
	v_lshlrev_b32_e32 v150, 16, v71
	v_and_b32_e32 v151, 0xffff0000, v71
	v_mul_f32_e32 v67, v148, v150
	v_mul_f32_e32 v71, v149, v151
	v_lshlrev_b32_e32 v148, 16, v76
	v_and_b32_e32 v149, 0xffff0000, v76
	v_lshlrev_b32_e32 v150, 16, v80
	v_and_b32_e32 v151, 0xffff0000, v80
	v_mul_f32_e32 v76, v148, v150
	v_mul_f32_e32 v80, v149, v151
	v_lshlrev_b32_e32 v148, 16, v77
	v_and_b32_e32 v149, 0xffff0000, v77
	v_lshlrev_b32_e32 v150, 16, v81
	v_and_b32_e32 v151, 0xffff0000, v81
	v_mul_f32_e32 v77, v148, v150
	v_mul_f32_e32 v81, v149, v151
	v_lshlrev_b32_e32 v148, 16, v78
	v_and_b32_e32 v149, 0xffff0000, v78
	v_lshlrev_b32_e32 v150, 16, v82
	v_and_b32_e32 v151, 0xffff0000, v82
	v_mul_f32_e32 v78, v148, v150
	v_mul_f32_e32 v82, v149, v151
	v_lshlrev_b32_e32 v148, 16, v79
	v_and_b32_e32 v149, 0xffff0000, v79
	v_lshlrev_b32_e32 v150, 16, v83
	v_and_b32_e32 v151, 0xffff0000, v83
	v_mul_f32_e32 v79, v148, v150
	v_mul_f32_e32 v83, v149, v151
	v_lshlrev_b32_e32 v148, 16, v88
	v_and_b32_e32 v149, 0xffff0000, v88
	v_lshlrev_b32_e32 v150, 16, v92
	v_and_b32_e32 v151, 0xffff0000, v92
	v_mul_f32_e32 v88, v148, v150
	v_mul_f32_e32 v92, v149, v151
	v_lshlrev_b32_e32 v148, 16, v89
	v_and_b32_e32 v149, 0xffff0000, v89
	v_lshlrev_b32_e32 v150, 16, v93
	v_and_b32_e32 v151, 0xffff0000, v93
	v_mul_f32_e32 v89, v148, v150
	v_mul_f32_e32 v93, v149, v151
	v_lshlrev_b32_e32 v148, 16, v90
	v_and_b32_e32 v149, 0xffff0000, v90
	v_lshlrev_b32_e32 v150, 16, v94
	v_and_b32_e32 v151, 0xffff0000, v94
	v_mul_f32_e32 v90, v148, v150
	v_mul_f32_e32 v94, v149, v151
	v_lshlrev_b32_e32 v148, 16, v91
	v_and_b32_e32 v149, 0xffff0000, v91
	v_lshlrev_b32_e32 v150, 16, v95
	v_and_b32_e32 v151, 0xffff0000, v95
	v_mul_f32_e32 v91, v148, v150
	v_mul_f32_e32 v95, v149, v151
	v_lshlrev_b32_e32 v148, 16, v100
	v_and_b32_e32 v149, 0xffff0000, v100
	v_lshlrev_b32_e32 v150, 16, v104
	v_and_b32_e32 v151, 0xffff0000, v104
	v_mul_f32_e32 v100, v148, v150
	v_mul_f32_e32 v104, v149, v151
	v_lshlrev_b32_e32 v148, 16, v101
	v_and_b32_e32 v149, 0xffff0000, v101
	v_lshlrev_b32_e32 v150, 16, v105
	v_and_b32_e32 v151, 0xffff0000, v105
	v_mul_f32_e32 v101, v148, v150
	v_mul_f32_e32 v105, v149, v151
	v_lshlrev_b32_e32 v148, 16, v102
	v_and_b32_e32 v149, 0xffff0000, v102
	v_lshlrev_b32_e32 v150, 16, v106
	v_and_b32_e32 v151, 0xffff0000, v106
	v_mul_f32_e32 v102, v148, v150
	v_mul_f32_e32 v106, v149, v151
	v_lshlrev_b32_e32 v148, 16, v103
	v_and_b32_e32 v149, 0xffff0000, v103
	v_lshlrev_b32_e32 v150, 16, v107
	v_and_b32_e32 v151, 0xffff0000, v107
	v_mul_f32_e32 v103, v148, v150
	v_mul_f32_e32 v107, v149, v151
	v_lshlrev_b32_e32 v148, 16, v112
	v_and_b32_e32 v149, 0xffff0000, v112
	v_lshlrev_b32_e32 v150, 16, v116
	v_and_b32_e32 v151, 0xffff0000, v116
	v_mul_f32_e32 v112, v148, v150
	v_mul_f32_e32 v116, v149, v151
	v_lshlrev_b32_e32 v148, 16, v113
	v_and_b32_e32 v149, 0xffff0000, v113
	v_lshlrev_b32_e32 v150, 16, v117
	v_and_b32_e32 v151, 0xffff0000, v117
	v_mul_f32_e32 v113, v148, v150
	v_mul_f32_e32 v117, v149, v151
	v_lshlrev_b32_e32 v148, 16, v114
	v_and_b32_e32 v149, 0xffff0000, v114
	v_lshlrev_b32_e32 v150, 16, v118
	v_and_b32_e32 v151, 0xffff0000, v118
	v_mul_f32_e32 v114, v148, v150
	v_mul_f32_e32 v118, v149, v151
	v_lshlrev_b32_e32 v148, 16, v115
	v_and_b32_e32 v149, 0xffff0000, v115
	v_lshlrev_b32_e32 v150, 16, v119
	v_and_b32_e32 v151, 0xffff0000, v119
	v_mul_f32_e32 v115, v148, v150
	v_mul_f32_e32 v119, v149, v151
	v_lshlrev_b32_e32 v148, 16, v124
	v_and_b32_e32 v149, 0xffff0000, v124
	v_lshlrev_b32_e32 v150, 16, v128
	v_and_b32_e32 v151, 0xffff0000, v128
	v_mul_f32_e32 v124, v148, v150
	v_mul_f32_e32 v128, v149, v151
	v_lshlrev_b32_e32 v148, 16, v125
	v_and_b32_e32 v149, 0xffff0000, v125
	v_lshlrev_b32_e32 v150, 16, v129
	v_and_b32_e32 v151, 0xffff0000, v129
	v_mul_f32_e32 v125, v148, v150
	v_mul_f32_e32 v129, v149, v151
	v_lshlrev_b32_e32 v148, 16, v126
	v_and_b32_e32 v149, 0xffff0000, v126
	v_lshlrev_b32_e32 v150, 16, v130
	v_and_b32_e32 v151, 0xffff0000, v130
	v_mul_f32_e32 v126, v148, v150
	v_mul_f32_e32 v130, v149, v151
	v_lshlrev_b32_e32 v148, 16, v127
	v_and_b32_e32 v149, 0xffff0000, v127
	v_lshlrev_b32_e32 v150, 16, v131
	v_and_b32_e32 v151, 0xffff0000, v131
	v_mul_f32_e32 v127, v148, v150
	v_mul_f32_e32 v131, v149, v151
	v_lshlrev_b32_e32 v148, 16, v136
	v_and_b32_e32 v149, 0xffff0000, v136
	v_lshlrev_b32_e32 v150, 16, v140
	v_and_b32_e32 v151, 0xffff0000, v140
	v_mul_f32_e32 v136, v148, v150
	v_mul_f32_e32 v140, v149, v151
	v_lshlrev_b32_e32 v148, 16, v137
	v_and_b32_e32 v149, 0xffff0000, v137
	v_lshlrev_b32_e32 v150, 16, v141
	v_and_b32_e32 v151, 0xffff0000, v141
	v_mul_f32_e32 v137, v148, v150
	v_mul_f32_e32 v141, v149, v151
	v_lshlrev_b32_e32 v148, 16, v138
	v_and_b32_e32 v149, 0xffff0000, v138
	v_lshlrev_b32_e32 v150, 16, v142
	v_and_b32_e32 v151, 0xffff0000, v142
	v_mul_f32_e32 v138, v148, v150
	v_mul_f32_e32 v142, v149, v151
	v_lshlrev_b32_e32 v148, 16, v139
	v_and_b32_e32 v149, 0xffff0000, v139
	v_lshlrev_b32_e32 v150, 16, v143
	v_and_b32_e32 v151, 0xffff0000, v143
	v_mul_f32_e32 v139, v148, v150
	v_mul_f32_e32 v143, v149, v151
	v_mul_f32_e32 v148, v16, v44
	v_mul_f32_e32 v149, v17, v48
	v_lshlrev_b32_e32 v150, 16, v60
	v_and_b32_e32 v151, 0xffff0000, v60
	v_fmac_f32_e32 v148, v8, v36
	v_fmac_f32_e32 v149, v9, v40
	v_fmac_f32_e32 v148, v24, v52
	v_fmac_f32_e32 v149, v25, v56
; __device__ __forceinline__ unsigned pkbf(float lo, float hi) { return pg8::cvt_pk_bf16(lo, hi); }
; __device__ __forceinline__ float bflo(unsigned w) { return __uint_as_float(w << 16); }
; __device__ __forceinline__ float bfhi(unsigned w) { return __uint_as_float(w & 0xffff0000u); }
; __device__ __forceinline__ void conv_phase(const bf16* BCU, const float* conv_w, bf16* MIX, int G, int bid, int tid) {
;     ...
;             const v4u bb = *(const v4u*)(base + (size_t)i * 3072);
;             float y[8];
; #pragma unroll
;             for (int e = 0; e < 8; ++e) y[e] = w0[e] * zp[e] + w1[e] * zc[e] + w2[e] * zn[e];
;             v4u o; o.x = pkbf(bflo(bb.x) * y[0], bfhi(bb.x) * y[1]); o.y = pkbf(bflo(bb.y) * y[2], bfhi(bb.y) * y[3]);
;             o.z = pkbf(bflo(bb.z) * y[4], bfhi(bb.z) * y[5]); o.w = pkbf(bflo(bb.w) * y[6], bfhi(bb.w) * y[7]);
;             *(v4u*)(MIX + (size_t)(t0 + i) * D + 1024 + ch) = o;
; #pragma unroll
;             for (int e = 0; e < 8; ++e) { zp[e] = zc[e]; zc[e] = zn[e]; }
	v_mul_f32_e32 v148, v150, v148
	v_mul_f32_e32 v149, v151, v149
	v_cvt_pk_bf16_f32 v156, v148, v149
	v_mul_f32_e32 v148, v18, v45
	v_mul_f32_e32 v149, v19, v49
	v_lshlrev_b32_e32 v150, 16, v61
	v_and_b32_e32 v151, 0xffff0000, v61
	v_fmac_f32_e32 v148, v10, v37
	v_fmac_f32_e32 v149, v11, v41
	v_fmac_f32_e32 v148, v26, v53
	v_fmac_f32_e32 v149, v27, v57
	v_mul_f32_e32 v148, v150, v148
	v_mul_f32_e32 v149, v151, v149
	v_cvt_pk_bf16_f32 v157, v148, v149
	v_mul_f32_e32 v148, v20, v46
	v_mul_f32_e32 v149, v21, v50
	v_lshlrev_b32_e32 v150, 16, v62
	v_and_b32_e32 v151, 0xffff0000, v62
	v_fmac_f32_e32 v148, v12, v38
	v_fmac_f32_e32 v149, v13, v42
	v_fmac_f32_e32 v148, v28, v54
	v_fmac_f32_e32 v149, v29, v58
	v_mul_f32_e32 v148, v150, v148
	v_mul_f32_e32 v149, v151, v149
	v_cvt_pk_bf16_f32 v158, v148, v149
	v_mul_f32_e32 v148, v22, v47
	v_mul_f32_e32 v149, v23, v51
	v_lshlrev_b32_e32 v150, 16, v63
	v_and_b32_e32 v151, 0xffff0000, v63
	v_fmac_f32_e32 v148, v14, v39
	v_fmac_f32_e32 v149, v15, v43
	v_fmac_f32_e32 v148, v30, v55
	v_fmac_f32_e32 v149, v31, v59
	v_mul_f32_e32 v148, v150, v148
	v_mul_f32_e32 v149, v151, v149
	v_cvt_pk_bf16_f32 v159, v148, v149
	global_store_dwordx4 v32, v[156:159], s[14:15] offset:2048
	v_add_u32_e32 v32, 0x1000, v32
	v_mul_f32_e32 v148, v16, v52
	v_mul_f32_e32 v149, v17, v56
	v_lshlrev_b32_e32 v150, 16, v72
	v_and_b32_e32 v151, 0xffff0000, v72
	v_fmac_f32_e32 v148, v8, v44
	v_fmac_f32_e32 v149, v9, v48
	v_fmac_f32_e32 v148, v24, v64
	v_fmac_f32_e32 v149, v25, v68
	v_mul_f32_e32 v148, v150, v148
	v_mul_f32_e32 v149, v151, v149
	v_cvt_pk_bf16_f32 v160, v148, v149
	v_mul_f32_e32 v148, v18, v53
	v_mul_f32_e32 v149, v19, v57
	v_lshlrev_b32_e32 v150, 16, v73
	v_and_b32_e32 v151, 0xffff0000, v73
	v_fmac_f32_e32 v148, v10, v45
	v_fmac_f32_e32 v149, v11, v49
	v_fmac_f32_e32 v148, v26, v65
	v_fmac_f32_e32 v149, v27, v69
	v_mul_f32_e32 v148, v150, v148
	v_mul_f32_e32 v149, v151, v149
	v_cvt_pk_bf16_f32 v161, v148, v149
	v_mul_f32_e32 v148, v20, v54
	v_mul_f32_e32 v149, v21, v58
	v_lshlrev_b32_e32 v150, 16, v74
	v_and_b32_e32 v151, 0xffff0000, v74
	v_fmac_f32_e32 v148, v12, v46
	v_fmac_f32_e32 v149, v13, v50
	v_fmac_f32_e32 v148, v28, v66
	v_fmac_f32_e32 v149, v29, v70
	v_mul_f32_e32 v148, v150, v148
	v_mul_f32_e32 v149, v151, v149
	v_cvt_pk_bf16_f32 v162, v148, v149
	v_mul_f32_e32 v148, v22, v55
	v_mul_f32_e32 v149, v23, v59
	v_lshlrev_b32_e32 v150, 16, v75
	v_and_b32_e32 v151, 0xffff0000, v75
	v_fmac_f32_e32 v148, v14, v47
	v_fmac_f32_e32 v149, v15, v51
	v_fmac_f32_e32 v148, v30, v67
	v_fmac_f32_e32 v149, v31, v71
	v_mul_f32_e32 v148, v150, v148
	v_mul_f32_e32 v149, v151, v149
	v_cvt_pk_bf16_f32 v163, v148, v149
	global_store_dwordx4 v32, v[160:163], s[14:15] offset:2048
	v_add_u32_e32 v32, 0x1000, v32
	v_mul_f32_e32 v148, v16, v64
	v_mul_f32_e32 v149, v17, v68
	v_lshlrev_b32_e32 v150, 16, v84
	v_and_b32_e32 v151, 0xffff0000, v84
	v_fmac_f32_e32 v148, v8, v52
	v_fmac_f32_e32 v149, v9, v56
	v_fmac_f32_e32 v148, v24, v76
	v_fmac_f32_e32 v149, v25, v80
	v_mul_f32_e32 v148, v150, v148
	v_mul_f32_e32 v149, v151, v149
	v_cvt_pk_bf16_f32 v156, v148, v149
	v_mul_f32_e32 v148, v18, v65
	v_mul_f32_e32 v149, v19, v69
	v_lshlrev_b32_e32 v150, 16, v85
	v_and_b32_e32 v151, 0xffff0000, v85
	v_fmac_f32_e32 v148, v10, v53
	v_fmac_f32_e32 v149, v11, v57
	v_fmac_f32_e32 v148, v26, v77
	v_fmac_f32_e32 v149, v27, v81
	v_mul_f32_e32 v148, v150, v148
	v_mul_f32_e32 v149, v151, v149
	v_cvt_pk_bf16_f32 v157, v148, v149
	v_mul_f32_e32 v148, v20, v66
	v_mul_f32_e32 v149, v21, v70
	v_lshlrev_b32_e32 v150, 16, v86
	v_and_b32_e32 v151, 0xffff0000, v86
	v_fmac_f32_e32 v148, v12, v54
	v_fmac_f32_e32 v149, v13, v58
	v_fmac_f32_e32 v148, v28, v78
	v_fmac_f32_e32 v149, v29, v82
	v_mul_f32_e32 v148, v150, v148
	v_mul_f32_e32 v149, v151, v149
	v_cvt_pk_bf16_f32 v158, v148, v149
	v_mul_f32_e32 v148, v22, v67
	v_mul_f32_e32 v149, v23, v71
	v_lshlrev_b32_e32 v150, 16, v87
	v_and_b32_e32 v151, 0xffff0000, v87
	v_fmac_f32_e32 v148, v14, v55
	v_fmac_f32_e32 v149, v15, v59
	v_fmac_f32_e32 v148, v30, v79
	v_fmac_f32_e32 v149, v31, v83
	v_mul_f32_e32 v148, v150, v148
	v_mul_f32_e32 v149, v151, v149
	v_cvt_pk_bf16_f32 v159, v148, v149
	global_store_dwordx4 v32, v[156:159], s[14:15] offset:2048
	v_add_u32_e32 v32, 0x1000, v32
	v_mul_f32_e32 v148, v16, v76
	v_mul_f32_e32 v149, v17, v80
	v_lshlrev_b32_e32 v150, 16, v96
	v_and_b32_e32 v151, 0xffff0000, v96
	v_fmac_f32_e32 v148, v8, v64
	v_fmac_f32_e32 v149, v9, v68
	v_fmac_f32_e32 v148, v24, v88
	v_fmac_f32_e32 v149, v25, v92
	v_mul_f32_e32 v148, v150, v148
	v_mul_f32_e32 v149, v151, v149
	v_cvt_pk_bf16_f32 v160, v148, v149
	v_mul_f32_e32 v148, v18, v77
	v_mul_f32_e32 v149, v19, v81
	v_lshlrev_b32_e32 v150, 16, v97
	v_and_b32_e32 v151, 0xffff0000, v97
	v_fmac_f32_e32 v148, v10, v65
	v_fmac_f32_e32 v149, v11, v69
	v_fmac_f32_e32 v148, v26, v89
	v_fmac_f32_e32 v149, v27, v93
	v_mul_f32_e32 v148, v150, v148
	v_mul_f32_e32 v149, v151, v149
	v_cvt_pk_bf16_f32 v161, v148, v149
	v_mul_f32_e32 v148, v20, v78
	v_mul_f32_e32 v149, v21, v82
	v_lshlrev_b32_e32 v150, 16, v98
	v_and_b32_e32 v151, 0xffff0000, v98
	v_fmac_f32_e32 v148, v12, v66
	v_fmac_f32_e32 v149, v13, v70
	v_fmac_f32_e32 v148, v28, v90
	v_fmac_f32_e32 v149, v29, v94
	v_mul_f32_e32 v148, v150, v148
	v_mul_f32_e32 v149, v151, v149
	v_cvt_pk_bf16_f32 v162, v148, v149
	v_mul_f32_e32 v148, v22, v79
	v_mul_f32_e32 v149, v23, v83
	v_lshlrev_b32_e32 v150, 16, v99
	v_and_b32_e32 v151, 0xffff0000, v99
	v_fmac_f32_e32 v148, v14, v67
	v_fmac_f32_e32 v149, v15, v71
	v_fmac_f32_e32 v148, v30, v91
	v_fmac_f32_e32 v149, v31, v95
	v_mul_f32_e32 v148, v150, v148
	v_mul_f32_e32 v149, v151, v149
; __device__ __forceinline__ unsigned pkbf(float lo, float hi) { return pg8::cvt_pk_bf16(lo, hi); }
; __device__ __forceinline__ float bflo(unsigned w) { return __uint_as_float(w << 16); }
; __device__ __forceinline__ float bfhi(unsigned w) { return __uint_as_float(w & 0xffff0000u); }
; __device__ __forceinline__ void conv_phase(const bf16* BCU, const float* conv_w, bf16* MIX, int G, int bid, int tid) {
;     ...
;             const v4u bb = *(const v4u*)(base + (size_t)i * 3072);
;             float y[8];
; #pragma unroll
;             for (int e = 0; e < 8; ++e) y[e] = w0[e] * zp[e] + w1[e] * zc[e] + w2[e] * zn[e];
;             v4u o; o.x = pkbf(bflo(bb.x) * y[0], bfhi(bb.x) * y[1]); o.y = pkbf(bflo(bb.y) * y[2], bfhi(bb.y) * y[3]);
;             o.z = pkbf(bflo(bb.z) * y[4], bfhi(bb.z) * y[5]); o.w = pkbf(bflo(bb.w) * y[6], bfhi(bb.w) * y[7]);
;             *(v4u*)(MIX + (size_t)(t0 + i) * D + 1024 + ch) = o;
; #pragma unroll
;             for (int e = 0; e < 8; ++e) { zp[e] = zc[e]; zc[e] = zn[e]; }
	v_cvt_pk_bf16_f32 v163, v148, v149
	global_store_dwordx4 v32, v[160:163], s[14:15] offset:2048
	v_add_u32_e32 v32, 0x1000, v32
	v_mul_f32_e32 v148, v16, v88
	v_mul_f32_e32 v149, v17, v92
	v_lshlrev_b32_e32 v150, 16, v108
	v_and_b32_e32 v151, 0xffff0000, v108
	v_fmac_f32_e32 v148, v8, v76
	v_fmac_f32_e32 v149, v9, v80
	v_fmac_f32_e32 v148, v24, v100
	v_fmac_f32_e32 v149, v25, v104
	v_mul_f32_e32 v148, v150, v148
	v_mul_f32_e32 v149, v151, v149
	v_cvt_pk_bf16_f32 v156, v148, v149
	v_mul_f32_e32 v148, v18, v89
	v_mul_f32_e32 v149, v19, v93
	v_lshlrev_b32_e32 v150, 16, v109
	v_and_b32_e32 v151, 0xffff0000, v109
	v_fmac_f32_e32 v148, v10, v77
	v_fmac_f32_e32 v149, v11, v81
	v_fmac_f32_e32 v148, v26, v101
	v_fmac_f32_e32 v149, v27, v105
	v_mul_f32_e32 v148, v150, v148
	v_mul_f32_e32 v149, v151, v149
	v_cvt_pk_bf16_f32 v157, v148, v149
	v_mul_f32_e32 v148, v20, v90
	v_mul_f32_e32 v149, v21, v94
	v_lshlrev_b32_e32 v150, 16, v110
	v_and_b32_e32 v151, 0xffff0000, v110
	v_fmac_f32_e32 v148, v12, v78
	v_fmac_f32_e32 v149, v13, v82
	v_fmac_f32_e32 v148, v28, v102
	v_fmac_f32_e32 v149, v29, v106
	v_mul_f32_e32 v148, v150, v148
	v_mul_f32_e32 v149, v151, v149
	v_cvt_pk_bf16_f32 v158, v148, v149
	v_mul_f32_e32 v148, v22, v91
	v_mul_f32_e32 v149, v23, v95
	v_lshlrev_b32_e32 v150, 16, v111
	v_and_b32_e32 v151, 0xffff0000, v111
	v_fmac_f32_e32 v148, v14, v79
	v_fmac_f32_e32 v149, v15, v83
	v_fmac_f32_e32 v148, v30, v103
	v_fmac_f32_e32 v149, v31, v107
	v_mul_f32_e32 v148, v150, v148
	v_mul_f32_e32 v149, v151, v149
	v_cvt_pk_bf16_f32 v159, v148, v149
	global_store_dwordx4 v32, v[156:159], s[14:15] offset:2048
	v_add_u32_e32 v32, 0x1000, v32
	v_mul_f32_e32 v148, v16, v100
	v_mul_f32_e32 v149, v17, v104
	v_lshlrev_b32_e32 v150, 16, v120
	v_and_b32_e32 v151, 0xffff0000, v120
	v_fmac_f32_e32 v148, v8, v88
	v_fmac_f32_e32 v149, v9, v92
	v_fmac_f32_e32 v148, v24, v112
	v_fmac_f32_e32 v149, v25, v116
	v_mul_f32_e32 v148, v150, v148
	v_mul_f32_e32 v149, v151, v149
	v_cvt_pk_bf16_f32 v160, v148, v149
	v_mul_f32_e32 v148, v18, v101
	v_mul_f32_e32 v149, v19, v105
	v_lshlrev_b32_e32 v150, 16, v121
	v_and_b32_e32 v151, 0xffff0000, v121
	v_fmac_f32_e32 v148, v10, v89
	v_fmac_f32_e32 v149, v11, v93
	v_fmac_f32_e32 v148, v26, v113
	v_fmac_f32_e32 v149, v27, v117
	v_mul_f32_e32 v148, v150, v148
	v_mul_f32_e32 v149, v151, v149
	v_cvt_pk_bf16_f32 v161, v148, v149
	v_mul_f32_e32 v148, v20, v102
	v_mul_f32_e32 v149, v21, v106
	v_lshlrev_b32_e32 v150, 16, v122
	v_and_b32_e32 v151, 0xffff0000, v122
	v_fmac_f32_e32 v148, v12, v90
	v_fmac_f32_e32 v149, v13, v94
	v_fmac_f32_e32 v148, v28, v114
	v_fmac_f32_e32 v149, v29, v118
	v_mul_f32_e32 v148, v150, v148
	v_mul_f32_e32 v149, v151, v149
	v_cvt_pk_bf16_f32 v162, v148, v149
	v_mul_f32_e32 v148, v22, v103
	v_mul_f32_e32 v149, v23, v107
	v_lshlrev_b32_e32 v150, 16, v123
	v_and_b32_e32 v151, 0xffff0000, v123
	v_fmac_f32_e32 v148, v14, v91
	v_fmac_f32_e32 v149, v15, v95
	v_fmac_f32_e32 v148, v30, v115
	v_fmac_f32_e32 v149, v31, v119
	v_mul_f32_e32 v148, v150, v148
	v_mul_f32_e32 v149, v151, v149
	v_cvt_pk_bf16_f32 v163, v148, v149
	global_store_dwordx4 v32, v[160:163], s[14:15] offset:2048
	v_add_u32_e32 v32, 0x1000, v32
	v_mul_f32_e32 v148, v16, v112
	v_mul_f32_e32 v149, v17, v116
	v_lshlrev_b32_e32 v150, 16, v132
	v_and_b32_e32 v151, 0xffff0000, v132
	v_fmac_f32_e32 v148, v8, v100
	v_fmac_f32_e32 v149, v9, v104
	v_fmac_f32_e32 v148, v24, v124
	v_fmac_f32_e32 v149, v25, v128
	v_mul_f32_e32 v148, v150, v148
	v_mul_f32_e32 v149, v151, v149
	v_cvt_pk_bf16_f32 v156, v148, v149
	v_mul_f32_e32 v148, v18, v113
	v_mul_f32_e32 v149, v19, v117
	v_lshlrev_b32_e32 v150, 16, v133
	v_and_b32_e32 v151, 0xffff0000, v133
	v_fmac_f32_e32 v148, v10, v101
	v_fmac_f32_e32 v149, v11, v105
	v_fmac_f32_e32 v148, v26, v125
	v_fmac_f32_e32 v149, v27, v129
	v_mul_f32_e32 v148, v150, v148
	v_mul_f32_e32 v149, v151, v149
	v_cvt_pk_bf16_f32 v157, v148, v149
	v_mul_f32_e32 v148, v20, v114
	v_mul_f32_e32 v149, v21, v118
	v_lshlrev_b32_e32 v150, 16, v134
	v_and_b32_e32 v151, 0xffff0000, v134
	v_fmac_f32_e32 v148, v12, v102
	v_fmac_f32_e32 v149, v13, v106
	v_fmac_f32_e32 v148, v28, v126
	v_fmac_f32_e32 v149, v29, v130
	v_mul_f32_e32 v148, v150, v148
	v_mul_f32_e32 v149, v151, v149
	v_cvt_pk_bf16_f32 v158, v148, v149
	v_mul_f32_e32 v148, v22, v115
	v_mul_f32_e32 v149, v23, v119
	v_lshlrev_b32_e32 v150, 16, v135
	v_and_b32_e32 v151, 0xffff0000, v135
	v_fmac_f32_e32 v148, v14, v103
	v_fmac_f32_e32 v149, v15, v107
	v_fmac_f32_e32 v148, v30, v127
	v_fmac_f32_e32 v149, v31, v131
	v_mul_f32_e32 v148, v150, v148
	v_mul_f32_e32 v149, v151, v149
	v_cvt_pk_bf16_f32 v159, v148, v149
	global_store_dwordx4 v32, v[156:159], s[14:15] offset:2048
	v_add_u32_e32 v32, 0x1000, v32
	v_mul_f32_e32 v148, v16, v124
	v_mul_f32_e32 v149, v17, v128
	v_lshlrev_b32_e32 v150, 16, v144
	v_and_b32_e32 v151, 0xffff0000, v144
	v_fmac_f32_e32 v148, v8, v112
	v_fmac_f32_e32 v149, v9, v116
	v_fmac_f32_e32 v148, v24, v136
	v_fmac_f32_e32 v149, v25, v140
	v_mul_f32_e32 v148, v150, v148
	v_mul_f32_e32 v149, v151, v149
	v_cvt_pk_bf16_f32 v160, v148, v149
	v_mul_f32_e32 v148, v18, v125
	v_mul_f32_e32 v149, v19, v129
	v_lshlrev_b32_e32 v150, 16, v145
	v_and_b32_e32 v151, 0xffff0000, v145
	v_fmac_f32_e32 v148, v10, v113
	v_fmac_f32_e32 v149, v11, v117
	v_fmac_f32_e32 v148, v26, v137
	v_fmac_f32_e32 v149, v27, v141
	v_mul_f32_e32 v148, v150, v148
	v_mul_f32_e32 v149, v151, v149
	v_cvt_pk_bf16_f32 v161, v148, v149
	v_mul_f32_e32 v148, v20, v126
	v_mul_f32_e32 v149, v21, v130
	v_lshlrev_b32_e32 v150, 16, v146
	v_and_b32_e32 v151, 0xffff0000, v146
	v_fmac_f32_e32 v148, v12, v114
	v_fmac_f32_e32 v149, v13, v118
; __device__ __forceinline__ void conv_phase(const bf16* BCU, const float* conv_w, bf16* MIX, int G, int bid, int tid) {
;     ...
;         if (tl0 > 0) CONV_Z(zp, -1); else {
; #pragma unroll
;             for (int e = 0; e < 8; ++e) zp[e] = 0.f; }
;         CONV_Z(zc, 0);
; #pragma unroll 4
;         for (int i = 0; i < 16; ++i) {
;             if (tl0 + i + 1 < SEQ) CONV_Z(zn, i + 1); else {
; #pragma unroll
;                 for (int e = 0; e < 8; ++e) zn[e] = 0.f; }
;             const v4u bb = *(const v4u*)(base + (size_t)i * 3072);
;     ...
;             for (int e = 0; e < 8; ++e) { zp[e] = zc[e]; zc[e] = zn[e]; }
	v_fmac_f32_e32 v148, v28, v138
	v_fmac_f32_e32 v149, v29, v142
	v_mul_f32_e32 v148, v150, v148
	v_mul_f32_e32 v149, v151, v149
	v_cvt_pk_bf16_f32 v162, v148, v149
	v_mul_f32_e32 v148, v22, v127
	v_mul_f32_e32 v149, v23, v131
	v_lshlrev_b32_e32 v150, 16, v147
	v_and_b32_e32 v151, 0xffff0000, v147
	v_fmac_f32_e32 v148, v14, v115
	v_fmac_f32_e32 v149, v15, v119
	v_fmac_f32_e32 v148, v30, v139
	v_fmac_f32_e32 v149, v31, v143
	v_mul_f32_e32 v148, v150, v148
	v_mul_f32_e32 v149, v151, v149
	v_cvt_pk_bf16_f32 v163, v148, v149
	global_store_dwordx4 v32, v[160:163], s[14:15] offset:2048
	v_add_u32_e32 v32, 0x1000, v32
	v_mov_b32_e32 v36, v124
	v_mov_b32_e32 v37, v125
	v_mov_b32_e32 v38, v126
	v_mov_b32_e32 v39, v127
	v_mov_b32_e32 v40, v128
	v_mov_b32_e32 v41, v129
	v_mov_b32_e32 v42, v130
	v_mov_b32_e32 v43, v131
	v_mov_b32_e32 v44, v136
	v_mov_b32_e32 v45, v137
	v_mov_b32_e32 v46, v138
	v_mov_b32_e32 v47, v139
	v_mov_b32_e32 v48, v140
	v_mov_b32_e32 v49, v141
	v_mov_b32_e32 v50, v142
	v_mov_b32_e32 v51, v143
	global_load_dwordx4 v[60:63], v34, s[10:11] offset:-2048
	v_add_u32_e32 v34, 0x1800, v34
	global_load_dwordx4 v[52:55], v34, s[10:11]
	global_load_dwordx4 v[56:59], v34, s[10:11] offset:2048
	global_load_dwordx4 v[72:75], v34, s[10:11] offset:-2048
	v_add_u32_e32 v34, 0x1800, v34
	global_load_dwordx4 v[64:67], v34, s[10:11]
	global_load_dwordx4 v[68:71], v34, s[10:11] offset:2048
	global_load_dwordx4 v[84:87], v34, s[10:11] offset:-2048
	v_add_u32_e32 v34, 0x1800, v34
	global_load_dwordx4 v[76:79], v34, s[10:11]
	global_load_dwordx4 v[80:83], v34, s[10:11] offset:2048
	global_load_dwordx4 v[96:99], v34, s[10:11] offset:-2048
	v_add_u32_e32 v34, 0x1800, v34
	global_load_dwordx4 v[88:91], v34, s[10:11]
	global_load_dwordx4 v[92:95], v34, s[10:11] offset:2048
	global_load_dwordx4 v[108:111], v34, s[10:11] offset:-2048
	v_add_u32_e32 v34, 0x1800, v34
	global_load_dwordx4 v[100:103], v34, s[10:11]
	global_load_dwordx4 v[104:107], v34, s[10:11] offset:2048
	global_load_dwordx4 v[120:123], v34, s[10:11] offset:-2048
	v_add_u32_e32 v34, 0x1800, v34
	global_load_dwordx4 v[112:115], v34, s[10:11]
	global_load_dwordx4 v[116:119], v34, s[10:11] offset:2048
	global_load_dwordx4 v[132:135], v34, s[10:11] offset:-2048
	v_add_u32_e32 v34, 0x1800, v34
	global_load_dwordx4 v[124:127], v34, s[10:11]
	global_load_dwordx4 v[128:131], v34, s[10:11] offset:2048
	global_load_dwordx4 v[144:147], v34, s[10:11] offset:-2048
	v_add_u32_e32 v34, 0x1800, v34
	s_cmp_eq_u32 s2, 0x7f
	s_cbranch_scc1 .Lcv_h1z
	global_load_dwordx4 v[136:139], v34, s[10:11]
	global_load_dwordx4 v[140:143], v34, s[10:11] offset:2048
	s_branch .Lcv_h1d
.Lcv_h1z:
	v_mov_b32_e32 v136, 0
	v_mov_b32_e32 v137, 0
	v_mov_b32_e32 v138, 0
	v_mov_b32_e32 v139, 0
	v_mov_b32_e32 v140, 0
	v_mov_b32_e32 v141, 0
	v_mov_b32_e32 v142, 0
	v_mov_b32_e32 v143, 0
.Lcv_h1d:
	s_waitcnt vmcnt(0)
	v_lshlrev_b32_e32 v148, 16, v52
	v_and_b32_e32 v149, 0xffff0000, v52
	v_lshlrev_b32_e32 v150, 16, v56
	v_and_b32_e32 v151, 0xffff0000, v56
	v_mul_f32_e32 v52, v148, v150
	v_mul_f32_e32 v56, v149, v151
	v_lshlrev_b32_e32 v148, 16, v53
	v_and_b32_e32 v149, 0xffff0000, v53
	v_lshlrev_b32_e32 v150, 16, v57
	v_and_b32_e32 v151, 0xffff0000, v57
	v_mul_f32_e32 v53, v148, v150
	v_mul_f32_e32 v57, v149, v151
	v_lshlrev_b32_e32 v148, 16, v54
	v_and_b32_e32 v149, 0xffff0000, v54
	v_lshlrev_b32_e32 v150, 16, v58
	v_and_b32_e32 v151, 0xffff0000, v58
	v_mul_f32_e32 v54, v148, v150
	v_mul_f32_e32 v58, v149, v151
	v_lshlrev_b32_e32 v148, 16, v55
	v_and_b32_e32 v149, 0xffff0000, v55
	v_lshlrev_b32_e32 v150, 16, v59
	v_and_b32_e32 v151, 0xffff0000, v59
	v_mul_f32_e32 v55, v148, v150
	v_mul_f32_e32 v59, v149, v151
	v_lshlrev_b32_e32 v148, 16, v64
	v_and_b32_e32 v149, 0xffff0000, v64
	v_lshlrev_b32_e32 v150, 16, v68
	v_and_b32_e32 v151, 0xffff0000, v68
	v_mul_f32_e32 v64, v148, v150
	v_mul_f32_e32 v68, v149, v151
	v_lshlrev_b32_e32 v148, 16, v65
	v_and_b32_e32 v149, 0xffff0000, v65
	v_lshlrev_b32_e32 v150, 16, v69
	v_and_b32_e32 v151, 0xffff0000, v69
	v_mul_f32_e32 v65, v148, v150
	v_mul_f32_e32 v69, v149, v151
	v_lshlrev_b32_e32 v148, 16, v66
	v_and_b32_e32 v149, 0xffff0000, v66
	v_lshlrev_b32_e32 v150, 16, v70
	v_and_b32_e32 v151, 0xffff0000, v70
	v_mul_f32_e32 v66, v148, v150
	v_mul_f32_e32 v70, v149, v151
	v_lshlrev_b32_e32 v148, 16, v67
	v_and_b32_e32 v149, 0xffff0000, v67
	v_lshlrev_b32_e32 v150, 16, v71
	v_and_b32_e32 v151, 0xffff0000, v71
	v_mul_f32_e32 v67, v148, v150
	v_mul_f32_e32 v71, v149, v151
	v_lshlrev_b32_e32 v148, 16, v76
	v_and_b32_e32 v149, 0xffff0000, v76
	v_lshlrev_b32_e32 v150, 16, v80
	v_and_b32_e32 v151, 0xffff0000, v80
	v_mul_f32_e32 v76, v148, v150
	v_mul_f32_e32 v80, v149, v151
	v_lshlrev_b32_e32 v148, 16, v77
	v_and_b32_e32 v149, 0xffff0000, v77
	v_lshlrev_b32_e32 v150, 16, v81
	v_and_b32_e32 v151, 0xffff0000, v81
	v_mul_f32_e32 v77, v148, v150
	v_mul_f32_e32 v81, v149, v151
	v_lshlrev_b32_e32 v148, 16, v78
	v_and_b32_e32 v149, 0xffff0000, v78
	v_lshlrev_b32_e32 v150, 16, v82
	v_and_b32_e32 v151, 0xffff0000, v82
	v_mul_f32_e32 v78, v148, v150
	v_mul_f32_e32 v82, v149, v151
	v_lshlrev_b32_e32 v148, 16, v79
	v_and_b32_e32 v149, 0xffff0000, v79
	v_lshlrev_b32_e32 v150, 16, v83
	v_and_b32_e32 v151, 0xffff0000, v83
	v_mul_f32_e32 v79, v148, v150
	v_mul_f32_e32 v83, v149, v151
	v_lshlrev_b32_e32 v148, 16, v88
	v_and_b32_e32 v149, 0xffff0000, v88
	v_lshlrev_b32_e32 v150, 16, v92
	v_and_b32_e32 v151, 0xffff0000, v92
	v_mul_f32_e32 v88, v148, v150
	v_mul_f32_e32 v92, v149, v151
	v_lshlrev_b32_e32 v148, 16, v89
	v_and_b32_e32 v149, 0xffff0000, v89
	v_lshlrev_b32_e32 v150, 16, v93
	v_and_b32_e32 v151, 0xffff0000, v93
; __device__ __forceinline__ unsigned pkbf(float lo, float hi) { return pg8::cvt_pk_bf16(lo, hi); }
; __device__ __forceinline__ float bflo(unsigned w) { return __uint_as_float(w << 16); }
; __device__ __forceinline__ float bfhi(unsigned w) { return __uint_as_float(w & 0xffff0000u); }
; __device__ __forceinline__ void conv_phase(const bf16* BCU, const float* conv_w, bf16* MIX, int G, int bid, int tid) {
;     ...
;             for (int e = 0; e < 8; ++e) y[e] = w0[e] * zp[e] + w1[e] * zc[e] + w2[e] * zn[e];
;             v4u o; o.x = pkbf(bflo(bb.x) * y[0], bfhi(bb.x) * y[1]); o.y = pkbf(bflo(bb.y) * y[2], bfhi(bb.y) * y[3]);
;             o.z = pkbf(bflo(bb.z) * y[4], bfhi(bb.z) * y[5]); o.w = pkbf(bflo(bb.w) * y[6], bfhi(bb.w) * y[7]);
;             *(v4u*)(MIX + (size_t)(t0 + i) * D + 1024 + ch) = o;
	v_mul_f32_e32 v89, v148, v150
	v_mul_f32_e32 v93, v149, v151
	v_lshlrev_b32_e32 v148, 16, v90
	v_and_b32_e32 v149, 0xffff0000, v90
	v_lshlrev_b32_e32 v150, 16, v94
	v_and_b32_e32 v151, 0xffff0000, v94
	v_mul_f32_e32 v90, v148, v150
	v_mul_f32_e32 v94, v149, v151
	v_lshlrev_b32_e32 v148, 16, v91
	v_and_b32_e32 v149, 0xffff0000, v91
	v_lshlrev_b32_e32 v150, 16, v95
	v_and_b32_e32 v151, 0xffff0000, v95
	v_mul_f32_e32 v91, v148, v150
	v_mul_f32_e32 v95, v149, v151
	v_lshlrev_b32_e32 v148, 16, v100
	v_and_b32_e32 v149, 0xffff0000, v100
	v_lshlrev_b32_e32 v150, 16, v104
	v_and_b32_e32 v151, 0xffff0000, v104
	v_mul_f32_e32 v100, v148, v150
	v_mul_f32_e32 v104, v149, v151
	v_lshlrev_b32_e32 v148, 16, v101
	v_and_b32_e32 v149, 0xffff0000, v101
	v_lshlrev_b32_e32 v150, 16, v105
	v_and_b32_e32 v151, 0xffff0000, v105
	v_mul_f32_e32 v101, v148, v150
	v_mul_f32_e32 v105, v149, v151
	v_lshlrev_b32_e32 v148, 16, v102
	v_and_b32_e32 v149, 0xffff0000, v102
	v_lshlrev_b32_e32 v150, 16, v106
	v_and_b32_e32 v151, 0xffff0000, v106
	v_mul_f32_e32 v102, v148, v150
	v_mul_f32_e32 v106, v149, v151
	v_lshlrev_b32_e32 v148, 16, v103
	v_and_b32_e32 v149, 0xffff0000, v103
	v_lshlrev_b32_e32 v150, 16, v107
	v_and_b32_e32 v151, 0xffff0000, v107
	v_mul_f32_e32 v103, v148, v150
	v_mul_f32_e32 v107, v149, v151
	v_lshlrev_b32_e32 v148, 16, v112
	v_and_b32_e32 v149, 0xffff0000, v112
	v_lshlrev_b32_e32 v150, 16, v116
	v_and_b32_e32 v151, 0xffff0000, v116
	v_mul_f32_e32 v112, v148, v150
	v_mul_f32_e32 v116, v149, v151
	v_lshlrev_b32_e32 v148, 16, v113
	v_and_b32_e32 v149, 0xffff0000, v113
	v_lshlrev_b32_e32 v150, 16, v117
	v_and_b32_e32 v151, 0xffff0000, v117
	v_mul_f32_e32 v113, v148, v150
	v_mul_f32_e32 v117, v149, v151
	v_lshlrev_b32_e32 v148, 16, v114
	v_and_b32_e32 v149, 0xffff0000, v114
	v_lshlrev_b32_e32 v150, 16, v118
	v_and_b32_e32 v151, 0xffff0000, v118
	v_mul_f32_e32 v114, v148, v150
	v_mul_f32_e32 v118, v149, v151
	v_lshlrev_b32_e32 v148, 16, v115
	v_and_b32_e32 v149, 0xffff0000, v115
	v_lshlrev_b32_e32 v150, 16, v119
	v_and_b32_e32 v151, 0xffff0000, v119
	v_mul_f32_e32 v115, v148, v150
	v_mul_f32_e32 v119, v149, v151
	v_lshlrev_b32_e32 v148, 16, v124
	v_and_b32_e32 v149, 0xffff0000, v124
	v_lshlrev_b32_e32 v150, 16, v128
	v_and_b32_e32 v151, 0xffff0000, v128
	v_mul_f32_e32 v124, v148, v150
	v_mul_f32_e32 v128, v149, v151
	v_lshlrev_b32_e32 v148, 16, v125
	v_and_b32_e32 v149, 0xffff0000, v125
	v_lshlrev_b32_e32 v150, 16, v129
	v_and_b32_e32 v151, 0xffff0000, v129
	v_mul_f32_e32 v125, v148, v150
	v_mul_f32_e32 v129, v149, v151
	v_lshlrev_b32_e32 v148, 16, v126
	v_and_b32_e32 v149, 0xffff0000, v126
	v_lshlrev_b32_e32 v150, 16, v130
	v_and_b32_e32 v151, 0xffff0000, v130
	v_mul_f32_e32 v126, v148, v150
	v_mul_f32_e32 v130, v149, v151
	v_lshlrev_b32_e32 v148, 16, v127
	v_and_b32_e32 v149, 0xffff0000, v127
	v_lshlrev_b32_e32 v150, 16, v131
	v_and_b32_e32 v151, 0xffff0000, v131
	v_mul_f32_e32 v127, v148, v150
	v_mul_f32_e32 v131, v149, v151
	v_lshlrev_b32_e32 v148, 16, v136
	v_and_b32_e32 v149, 0xffff0000, v136
	v_lshlrev_b32_e32 v150, 16, v140
	v_and_b32_e32 v151, 0xffff0000, v140
	v_mul_f32_e32 v136, v148, v150
	v_mul_f32_e32 v140, v149, v151
	v_lshlrev_b32_e32 v148, 16, v137
	v_and_b32_e32 v149, 0xffff0000, v137
	v_lshlrev_b32_e32 v150, 16, v141
	v_and_b32_e32 v151, 0xffff0000, v141
	v_mul_f32_e32 v137, v148, v150
	v_mul_f32_e32 v141, v149, v151
	v_lshlrev_b32_e32 v148, 16, v138
	v_and_b32_e32 v149, 0xffff0000, v138
	v_lshlrev_b32_e32 v150, 16, v142
	v_and_b32_e32 v151, 0xffff0000, v142
	v_mul_f32_e32 v138, v148, v150
	v_mul_f32_e32 v142, v149, v151
	v_lshlrev_b32_e32 v148, 16, v139
	v_and_b32_e32 v149, 0xffff0000, v139
	v_lshlrev_b32_e32 v150, 16, v143
	v_and_b32_e32 v151, 0xffff0000, v143
	v_mul_f32_e32 v139, v148, v150
	v_mul_f32_e32 v143, v149, v151
	v_mul_f32_e32 v148, v16, v44
	v_mul_f32_e32 v149, v17, v48
	v_lshlrev_b32_e32 v150, 16, v60
	v_and_b32_e32 v151, 0xffff0000, v60
	v_fmac_f32_e32 v148, v8, v36
	v_fmac_f32_e32 v149, v9, v40
	v_fmac_f32_e32 v148, v24, v52
	v_fmac_f32_e32 v149, v25, v56
	v_mul_f32_e32 v148, v150, v148
	v_mul_f32_e32 v149, v151, v149
	v_cvt_pk_bf16_f32 v156, v148, v149
	v_mul_f32_e32 v148, v18, v45
	v_mul_f32_e32 v149, v19, v49
	v_lshlrev_b32_e32 v150, 16, v61
	v_and_b32_e32 v151, 0xffff0000, v61
	v_fmac_f32_e32 v148, v10, v37
	v_fmac_f32_e32 v149, v11, v41
	v_fmac_f32_e32 v148, v26, v53
	v_fmac_f32_e32 v149, v27, v57
	v_mul_f32_e32 v148, v150, v148
	v_mul_f32_e32 v149, v151, v149
	v_cvt_pk_bf16_f32 v157, v148, v149
	v_mul_f32_e32 v148, v20, v46
	v_mul_f32_e32 v149, v21, v50
	v_lshlrev_b32_e32 v150, 16, v62
	v_and_b32_e32 v151, 0xffff0000, v62
	v_fmac_f32_e32 v148, v12, v38
	v_fmac_f32_e32 v149, v13, v42
	v_fmac_f32_e32 v148, v28, v54
	v_fmac_f32_e32 v149, v29, v58
	v_mul_f32_e32 v148, v150, v148
	v_mul_f32_e32 v149, v151, v149
	v_cvt_pk_bf16_f32 v158, v148, v149
	v_mul_f32_e32 v148, v22, v47
	v_mul_f32_e32 v149, v23, v51
	v_lshlrev_b32_e32 v150, 16, v63
	v_and_b32_e32 v151, 0xffff0000, v63
	v_fmac_f32_e32 v148, v14, v39
	v_fmac_f32_e32 v149, v15, v43
	v_fmac_f32_e32 v148, v30, v55
	v_fmac_f32_e32 v149, v31, v59
	v_mul_f32_e32 v148, v150, v148
	v_mul_f32_e32 v149, v151, v149
	v_cvt_pk_bf16_f32 v159, v148, v149
	global_store_dwordx4 v32, v[156:159], s[14:15] offset:2048
	v_add_u32_e32 v32, 0x1000, v32
	v_mul_f32_e32 v148, v16, v52
	v_mul_f32_e32 v149, v17, v56
	v_lshlrev_b32_e32 v150, 16, v72
	v_and_b32_e32 v151, 0xffff0000, v72
	v_fmac_f32_e32 v148, v8, v44
	v_fmac_f32_e32 v149, v9, v48
	v_fmac_f32_e32 v148, v24, v64
	v_fmac_f32_e32 v149, v25, v68
	v_mul_f32_e32 v148, v150, v148
	v_mul_f32_e32 v149, v151, v149
	v_cvt_pk_bf16_f32 v160, v148, v149
; __device__ __forceinline__ unsigned pkbf(float lo, float hi) { return pg8::cvt_pk_bf16(lo, hi); }
; __device__ __forceinline__ float bflo(unsigned w) { return __uint_as_float(w << 16); }
; __device__ __forceinline__ float bfhi(unsigned w) { return __uint_as_float(w & 0xffff0000u); }
; __device__ __forceinline__ void conv_phase(const bf16* BCU, const float* conv_w, bf16* MIX, int G, int bid, int tid) {
;     ...
;             const v4u bb = *(const v4u*)(base + (size_t)i * 3072);
;             float y[8];
; #pragma unroll
;             for (int e = 0; e < 8; ++e) y[e] = w0[e] * zp[e] + w1[e] * zc[e] + w2[e] * zn[e];
;             v4u o; o.x = pkbf(bflo(bb.x) * y[0], bfhi(bb.x) * y[1]); o.y = pkbf(bflo(bb.y) * y[2], bfhi(bb.y) * y[3]);
;             o.z = pkbf(bflo(bb.z) * y[4], bfhi(bb.z) * y[5]); o.w = pkbf(bflo(bb.w) * y[6], bfhi(bb.w) * y[7]);
;             *(v4u*)(MIX + (size_t)(t0 + i) * D + 1024 + ch) = o;
; #pragma unroll
;             for (int e = 0; e < 8; ++e) { zp[e] = zc[e]; zc[e] = zn[e]; }
	v_mul_f32_e32 v148, v18, v53
	v_mul_f32_e32 v149, v19, v57
	v_lshlrev_b32_e32 v150, 16, v73
	v_and_b32_e32 v151, 0xffff0000, v73
	v_fmac_f32_e32 v148, v10, v45
	v_fmac_f32_e32 v149, v11, v49
	v_fmac_f32_e32 v148, v26, v65
	v_fmac_f32_e32 v149, v27, v69
	v_mul_f32_e32 v148, v150, v148
	v_mul_f32_e32 v149, v151, v149
	v_cvt_pk_bf16_f32 v161, v148, v149
	v_mul_f32_e32 v148, v20, v54
	v_mul_f32_e32 v149, v21, v58
	v_lshlrev_b32_e32 v150, 16, v74
	v_and_b32_e32 v151, 0xffff0000, v74
	v_fmac_f32_e32 v148, v12, v46
	v_fmac_f32_e32 v149, v13, v50
	v_fmac_f32_e32 v148, v28, v66
	v_fmac_f32_e32 v149, v29, v70
	v_mul_f32_e32 v148, v150, v148
	v_mul_f32_e32 v149, v151, v149
	v_cvt_pk_bf16_f32 v162, v148, v149
	v_mul_f32_e32 v148, v22, v55
	v_mul_f32_e32 v149, v23, v59
	v_lshlrev_b32_e32 v150, 16, v75
	v_and_b32_e32 v151, 0xffff0000, v75
	v_fmac_f32_e32 v148, v14, v47
	v_fmac_f32_e32 v149, v15, v51
	v_fmac_f32_e32 v148, v30, v67
	v_fmac_f32_e32 v149, v31, v71
	v_mul_f32_e32 v148, v150, v148
	v_mul_f32_e32 v149, v151, v149
	v_cvt_pk_bf16_f32 v163, v148, v149
	global_store_dwordx4 v32, v[160:163], s[14:15] offset:2048
	v_add_u32_e32 v32, 0x1000, v32
	v_mul_f32_e32 v148, v16, v64
	v_mul_f32_e32 v149, v17, v68
	v_lshlrev_b32_e32 v150, 16, v84
	v_and_b32_e32 v151, 0xffff0000, v84
	v_fmac_f32_e32 v148, v8, v52
	v_fmac_f32_e32 v149, v9, v56
	v_fmac_f32_e32 v148, v24, v76
	v_fmac_f32_e32 v149, v25, v80
	v_mul_f32_e32 v148, v150, v148
	v_mul_f32_e32 v149, v151, v149
	v_cvt_pk_bf16_f32 v156, v148, v149
	v_mul_f32_e32 v148, v18, v65
	v_mul_f32_e32 v149, v19, v69
	v_lshlrev_b32_e32 v150, 16, v85
	v_and_b32_e32 v151, 0xffff0000, v85
	v_fmac_f32_e32 v148, v10, v53
	v_fmac_f32_e32 v149, v11, v57
	v_fmac_f32_e32 v148, v26, v77
	v_fmac_f32_e32 v149, v27, v81
	v_mul_f32_e32 v148, v150, v148
	v_mul_f32_e32 v149, v151, v149
	v_cvt_pk_bf16_f32 v157, v148, v149
	v_mul_f32_e32 v148, v20, v66
	v_mul_f32_e32 v149, v21, v70
	v_lshlrev_b32_e32 v150, 16, v86
	v_and_b32_e32 v151, 0xffff0000, v86
	v_fmac_f32_e32 v148, v12, v54
	v_fmac_f32_e32 v149, v13, v58
	v_fmac_f32_e32 v148, v28, v78
	v_fmac_f32_e32 v149, v29, v82
	v_mul_f32_e32 v148, v150, v148
	v_mul_f32_e32 v149, v151, v149
	v_cvt_pk_bf16_f32 v158, v148, v149
	v_mul_f32_e32 v148, v22, v67
	v_mul_f32_e32 v149, v23, v71
	v_lshlrev_b32_e32 v150, 16, v87
	v_and_b32_e32 v151, 0xffff0000, v87
	v_fmac_f32_e32 v148, v14, v55
	v_fmac_f32_e32 v149, v15, v59
	v_fmac_f32_e32 v148, v30, v79
	v_fmac_f32_e32 v149, v31, v83
	v_mul_f32_e32 v148, v150, v148
	v_mul_f32_e32 v149, v151, v149
	v_cvt_pk_bf16_f32 v159, v148, v149
	global_store_dwordx4 v32, v[156:159], s[14:15] offset:2048
	v_add_u32_e32 v32, 0x1000, v32
	v_mul_f32_e32 v148, v16, v76
	v_mul_f32_e32 v149, v17, v80
	v_lshlrev_b32_e32 v150, 16, v96
	v_and_b32_e32 v151, 0xffff0000, v96
	v_fmac_f32_e32 v148, v8, v64
	v_fmac_f32_e32 v149, v9, v68
	v_fmac_f32_e32 v148, v24, v88
	v_fmac_f32_e32 v149, v25, v92
	v_mul_f32_e32 v148, v150, v148
	v_mul_f32_e32 v149, v151, v149
	v_cvt_pk_bf16_f32 v160, v148, v149
	v_mul_f32_e32 v148, v18, v77
	v_mul_f32_e32 v149, v19, v81
	v_lshlrev_b32_e32 v150, 16, v97
	v_and_b32_e32 v151, 0xffff0000, v97
	v_fmac_f32_e32 v148, v10, v65
	v_fmac_f32_e32 v149, v11, v69
	v_fmac_f32_e32 v148, v26, v89
	v_fmac_f32_e32 v149, v27, v93
	v_mul_f32_e32 v148, v150, v148
	v_mul_f32_e32 v149, v151, v149
	v_cvt_pk_bf16_f32 v161, v148, v149
	v_mul_f32_e32 v148, v20, v78
	v_mul_f32_e32 v149, v21, v82
	v_lshlrev_b32_e32 v150, 16, v98
	v_and_b32_e32 v151, 0xffff0000, v98
	v_fmac_f32_e32 v148, v12, v66
	v_fmac_f32_e32 v149, v13, v70
	v_fmac_f32_e32 v148, v28, v90
	v_fmac_f32_e32 v149, v29, v94
	v_mul_f32_e32 v148, v150, v148
	v_mul_f32_e32 v149, v151, v149
	v_cvt_pk_bf16_f32 v162, v148, v149
	v_mul_f32_e32 v148, v22, v79
	v_mul_f32_e32 v149, v23, v83
	v_lshlrev_b32_e32 v150, 16, v99
	v_and_b32_e32 v151, 0xffff0000, v99
	v_fmac_f32_e32 v148, v14, v67
	v_fmac_f32_e32 v149, v15, v71
	v_fmac_f32_e32 v148, v30, v91
	v_fmac_f32_e32 v149, v31, v95
	v_mul_f32_e32 v148, v150, v148
	v_mul_f32_e32 v149, v151, v149
	v_cvt_pk_bf16_f32 v163, v148, v149
	global_store_dwordx4 v32, v[160:163], s[14:15] offset:2048
	v_add_u32_e32 v32, 0x1000, v32
	v_mul_f32_e32 v148, v16, v88
	v_mul_f32_e32 v149, v17, v92
	v_lshlrev_b32_e32 v150, 16, v108
	v_and_b32_e32 v151, 0xffff0000, v108
	v_fmac_f32_e32 v148, v8, v76
	v_fmac_f32_e32 v149, v9, v80
	v_fmac_f32_e32 v148, v24, v100
	v_fmac_f32_e32 v149, v25, v104
	v_mul_f32_e32 v148, v150, v148
	v_mul_f32_e32 v149, v151, v149
	v_cvt_pk_bf16_f32 v156, v148, v149
	v_mul_f32_e32 v148, v18, v89
	v_mul_f32_e32 v149, v19, v93
	v_lshlrev_b32_e32 v150, 16, v109
	v_and_b32_e32 v151, 0xffff0000, v109
	v_fmac_f32_e32 v148, v10, v77
	v_fmac_f32_e32 v149, v11, v81
	v_fmac_f32_e32 v148, v26, v101
	v_fmac_f32_e32 v149, v27, v105
	v_mul_f32_e32 v148, v150, v148
	v_mul_f32_e32 v149, v151, v149
	v_cvt_pk_bf16_f32 v157, v148, v149
	v_mul_f32_e32 v148, v20, v90
	v_mul_f32_e32 v149, v21, v94
	v_lshlrev_b32_e32 v150, 16, v110
	v_and_b32_e32 v151, 0xffff0000, v110
	v_fmac_f32_e32 v148, v12, v78
	v_fmac_f32_e32 v149, v13, v82
	v_fmac_f32_e32 v148, v28, v102
	v_fmac_f32_e32 v149, v29, v106
	v_mul_f32_e32 v148, v150, v148
; __device__ __forceinline__ unsigned pkbf(float lo, float hi) { return pg8::cvt_pk_bf16(lo, hi); }
; __device__ __forceinline__ float bflo(unsigned w) { return __uint_as_float(w << 16); }
; __device__ __forceinline__ float bfhi(unsigned w) { return __uint_as_float(w & 0xffff0000u); }
; __device__ __forceinline__ void conv_phase(const bf16* BCU, const float* conv_w, bf16* MIX, int G, int bid, int tid) {
;     ...
;             const v4u bb = *(const v4u*)(base + (size_t)i * 3072);
;             float y[8];
; #pragma unroll
;             for (int e = 0; e < 8; ++e) y[e] = w0[e] * zp[e] + w1[e] * zc[e] + w2[e] * zn[e];
;             v4u o; o.x = pkbf(bflo(bb.x) * y[0], bfhi(bb.x) * y[1]); o.y = pkbf(bflo(bb.y) * y[2], bfhi(bb.y) * y[3]);
;             o.z = pkbf(bflo(bb.z) * y[4], bfhi(bb.z) * y[5]); o.w = pkbf(bflo(bb.w) * y[6], bfhi(bb.w) * y[7]);
;             *(v4u*)(MIX + (size_t)(t0 + i) * D + 1024 + ch) = o;
; #pragma unroll
;             for (int e = 0; e < 8; ++e) { zp[e] = zc[e]; zc[e] = zn[e]; }
;         }
	v_mul_f32_e32 v149, v151, v149
	v_cvt_pk_bf16_f32 v158, v148, v149
	v_mul_f32_e32 v148, v22, v91
	v_mul_f32_e32 v149, v23, v95
	v_lshlrev_b32_e32 v150, 16, v111
	v_and_b32_e32 v151, 0xffff0000, v111
	v_fmac_f32_e32 v148, v14, v79
	v_fmac_f32_e32 v149, v15, v83
	v_fmac_f32_e32 v148, v30, v103
	v_fmac_f32_e32 v149, v31, v107
	v_mul_f32_e32 v148, v150, v148
	v_mul_f32_e32 v149, v151, v149
	v_cvt_pk_bf16_f32 v159, v148, v149
	global_store_dwordx4 v32, v[156:159], s[14:15] offset:2048
	v_add_u32_e32 v32, 0x1000, v32
	v_mul_f32_e32 v148, v16, v100
	v_mul_f32_e32 v149, v17, v104
	v_lshlrev_b32_e32 v150, 16, v120
	v_and_b32_e32 v151, 0xffff0000, v120
	v_fmac_f32_e32 v148, v8, v88
	v_fmac_f32_e32 v149, v9, v92
	v_fmac_f32_e32 v148, v24, v112
	v_fmac_f32_e32 v149, v25, v116
	v_mul_f32_e32 v148, v150, v148
	v_mul_f32_e32 v149, v151, v149
	v_cvt_pk_bf16_f32 v160, v148, v149
	v_mul_f32_e32 v148, v18, v101
	v_mul_f32_e32 v149, v19, v105
	v_lshlrev_b32_e32 v150, 16, v121
	v_and_b32_e32 v151, 0xffff0000, v121
	v_fmac_f32_e32 v148, v10, v89
	v_fmac_f32_e32 v149, v11, v93
	v_fmac_f32_e32 v148, v26, v113
	v_fmac_f32_e32 v149, v27, v117
	v_mul_f32_e32 v148, v150, v148
	v_mul_f32_e32 v149, v151, v149
	v_cvt_pk_bf16_f32 v161, v148, v149
	v_mul_f32_e32 v148, v20, v102
	v_mul_f32_e32 v149, v21, v106
	v_lshlrev_b32_e32 v150, 16, v122
	v_and_b32_e32 v151, 0xffff0000, v122
	v_fmac_f32_e32 v148, v12, v90
	v_fmac_f32_e32 v149, v13, v94
	v_fmac_f32_e32 v148, v28, v114
	v_fmac_f32_e32 v149, v29, v118
	v_mul_f32_e32 v148, v150, v148
	v_mul_f32_e32 v149, v151, v149
	v_cvt_pk_bf16_f32 v162, v148, v149
	v_mul_f32_e32 v148, v22, v103
	v_mul_f32_e32 v149, v23, v107
	v_lshlrev_b32_e32 v150, 16, v123
	v_and_b32_e32 v151, 0xffff0000, v123
	v_fmac_f32_e32 v148, v14, v91
	v_fmac_f32_e32 v149, v15, v95
	v_fmac_f32_e32 v148, v30, v115
	v_fmac_f32_e32 v149, v31, v119
	v_mul_f32_e32 v148, v150, v148
	v_mul_f32_e32 v149, v151, v149
	v_cvt_pk_bf16_f32 v163, v148, v149
	global_store_dwordx4 v32, v[160:163], s[14:15] offset:2048
	v_add_u32_e32 v32, 0x1000, v32
	v_mul_f32_e32 v148, v16, v112
	v_mul_f32_e32 v149, v17, v116
	v_lshlrev_b32_e32 v150, 16, v132
	v_and_b32_e32 v151, 0xffff0000, v132
	v_fmac_f32_e32 v148, v8, v100
	v_fmac_f32_e32 v149, v9, v104
	v_fmac_f32_e32 v148, v24, v124
	v_fmac_f32_e32 v149, v25, v128
	v_mul_f32_e32 v148, v150, v148
	v_mul_f32_e32 v149, v151, v149
	v_cvt_pk_bf16_f32 v156, v148, v149
	v_mul_f32_e32 v148, v18, v113
	v_mul_f32_e32 v149, v19, v117
	v_lshlrev_b32_e32 v150, 16, v133
	v_and_b32_e32 v151, 0xffff0000, v133
	v_fmac_f32_e32 v148, v10, v101
	v_fmac_f32_e32 v149, v11, v105
	v_fmac_f32_e32 v148, v26, v125
	v_fmac_f32_e32 v149, v27, v129
	v_mul_f32_e32 v148, v150, v148
	v_mul_f32_e32 v149, v151, v149
	v_cvt_pk_bf16_f32 v157, v148, v149
	v_mul_f32_e32 v148, v20, v114
	v_mul_f32_e32 v149, v21, v118
	v_lshlrev_b32_e32 v150, 16, v134
	v_and_b32_e32 v151, 0xffff0000, v134
	v_fmac_f32_e32 v148, v12, v102
	v_fmac_f32_e32 v149, v13, v106
	v_fmac_f32_e32 v148, v28, v126
	v_fmac_f32_e32 v149, v29, v130
	v_mul_f32_e32 v148, v150, v148
	v_mul_f32_e32 v149, v151, v149
	v_cvt_pk_bf16_f32 v158, v148, v149
	v_mul_f32_e32 v148, v22, v115
	v_mul_f32_e32 v149, v23, v119
	v_lshlrev_b32_e32 v150, 16, v135
	v_and_b32_e32 v151, 0xffff0000, v135
	v_fmac_f32_e32 v148, v14, v103
	v_fmac_f32_e32 v149, v15, v107
	v_fmac_f32_e32 v148, v30, v127
	v_fmac_f32_e32 v149, v31, v131
	v_mul_f32_e32 v148, v150, v148
	v_mul_f32_e32 v149, v151, v149
	v_cvt_pk_bf16_f32 v159, v148, v149
	global_store_dwordx4 v32, v[156:159], s[14:15] offset:2048
	v_add_u32_e32 v32, 0x1000, v32
	v_mul_f32_e32 v148, v16, v124
	v_mul_f32_e32 v149, v17, v128
	v_lshlrev_b32_e32 v150, 16, v144
	v_and_b32_e32 v151, 0xffff0000, v144
	v_fmac_f32_e32 v148, v8, v112
	v_fmac_f32_e32 v149, v9, v116
	v_fmac_f32_e32 v148, v24, v136
	v_fmac_f32_e32 v149, v25, v140
	v_mul_f32_e32 v148, v150, v148
	v_mul_f32_e32 v149, v151, v149
	v_cvt_pk_bf16_f32 v160, v148, v149
	v_mul_f32_e32 v148, v18, v125
	v_mul_f32_e32 v149, v19, v129
	v_lshlrev_b32_e32 v150, 16, v145
	v_and_b32_e32 v151, 0xffff0000, v145
	v_fmac_f32_e32 v148, v10, v113
	v_fmac_f32_e32 v149, v11, v117
	v_fmac_f32_e32 v148, v26, v137
	v_fmac_f32_e32 v149, v27, v141
	v_mul_f32_e32 v148, v150, v148
	v_mul_f32_e32 v149, v151, v149
	v_cvt_pk_bf16_f32 v161, v148, v149
	v_mul_f32_e32 v148, v20, v126
	v_mul_f32_e32 v149, v21, v130
	v_lshlrev_b32_e32 v150, 16, v146
	v_and_b32_e32 v151, 0xffff0000, v146
	v_fmac_f32_e32 v148, v12, v114
	v_fmac_f32_e32 v149, v13, v118
	v_fmac_f32_e32 v148, v28, v138
	v_fmac_f32_e32 v149, v29, v142
	v_mul_f32_e32 v148, v150, v148
	v_mul_f32_e32 v149, v151, v149
	v_cvt_pk_bf16_f32 v162, v148, v149
	v_mul_f32_e32 v148, v22, v127
	v_mul_f32_e32 v149, v23, v131
	v_lshlrev_b32_e32 v150, 16, v147
	v_and_b32_e32 v151, 0xffff0000, v147
	v_fmac_f32_e32 v148, v14, v115
	v_fmac_f32_e32 v149, v15, v119
	v_fmac_f32_e32 v148, v30, v139
	v_fmac_f32_e32 v149, v31, v143
	v_mul_f32_e32 v148, v150, v148
	v_mul_f32_e32 v149, v151, v149
	v_cvt_pk_bf16_f32 v163, v148, v149
	global_store_dwordx4 v32, v[160:163], s[14:15] offset:2048
	v_add_u32_e32 v32, 0x1000, v32
	v_mov_b32_e32 v74, v152
	s_branch .LBB0_247
